# GEMM K-loop: four loop-invariant LDS base adds folded into ds_read offset immediates (one base VGPR set per K pass)
# speedup vs baseline: 1.0005x; 1.0005x over previous
; #define PG8_STAGE(bufoff, gbase, voff) do { _Pragma("unroll") for (int _i = 0; _i < 2; ++_i) \
;         __builtin_amdgcn_global_load_lds((const unsigned*)((const char*)(gbase) + (voff)[_i]), (LAS unsigned*)(lds + (bufoff) + ldsw + _i * 8192), 16, 0, 0); } while (0)
; #define PG8_LDA(dst, b, h) do { _Pragma("unroll") for (int m = 0; m < 4; ++m) _Pragma("unroll") for (int k = 0; k < 2; ++k) dst[m][k] = *(const LAS bf16x8*)(lds + PG8_SA(b, h) + aoff + m * 2048 + k * 1024); } while (0)
; #define PG8_LDB(dst, b, h) do { _Pragma("unroll") for (int n = 0; n < 2; ++n) _Pragma("unroll") for (int k = 0; k < 2; ++k) dst[n][k] = *(const LAS bf16x8*)(lds + PG8_SB(b, h) + boff + n * 2048 + k * 1024); } while (0)
; #define PG8_WAIT_V(n) asm volatile("s_waitcnt vmcnt(" #n ")" ::: "memory")
; #define PG8_WAIT_L(n) asm volatile("s_waitcnt lgkmcnt(" #n ")" ::: "memory")
; #define PG8_BAR __builtin_amdgcn_s_barrier()
; template <class Epi>
; __device__ __forceinline__ void gemm_phase(LAS unsigned char* lds, const Gemm g, const StaticOrder& S, const Epi& E) {
;     ...
;         const bool lastpass = (pass == npass - 1);
;         if (!lastpass) { nA = (const char*)g.A2 + (size_t)cur.pm * tstepA; nB = (const char*)g.Bt2 + (size_t)cur.pn * tstepB; }
;         else if (has_next) { nA = (const char*)g.A + (size_t)nxt.pm * tstepA; nB = (const char*)g.Bt + (size_t)nxt.pn * tstepB; }
;         else { nA = cA; nB = cB; }
;         for (int t = 0; t < nt; t += 2) {
;             const bool last = (t == nt - 2);
;             const char* a1 = cA + (size_t)(t + 1) * kstep;
;             const char* a2 = last ? nA : cA + (size_t)(t + 2) * kstep; const char* b2 = last ? nB : cB + (size_t)(t + 2) * kstep;
;             const char* a3 = a2 + kstep; const char* b3 = b2 + kstep;
;             PG8_LDB(B0, 0, 0); PG8_SCHED; PG8_LDA(At, 0, 0); PG8_STAGE(PG8_SA(1, 1), a1 + hstepA, voffA);
;             PG8_WAIT_L(8); PG8_BAR; PG8_WAIT_L(0); PG8_MMA(0, 0, At, B0); PG8_BAR; PG8_SCHED;
;             PG8_LDB(B1, 0, 1); PG8_STAGE(PG8_SB(0, 0), b2, voffB);
;             PG8_BAR; PG8_WAIT_L(0); PG8_MMA(0, 1, At, B1); PG8_BAR;
;             PG8_LDA(At, 0, 1); PG8_STAGE(PG8_SA(0, 0), a2, voffA);
;             PG8_BAR; PG8_WAIT_L(0); PG8_MMA(1, 0, At, B0); PG8_BAR; PG8_SCHED;
;             PG8_STAGE(PG8_SB(0, 1), b2 + hstepB, voffB);
;             PG8_WAIT_V(6); PG8_BAR; PG8_MMA(1, 1, At, B1); PG8_BAR;
.LBB0_301:
	s_add_u32 vcc_lo, s64, 0x100
	s_addc_u32 vcc_hi, s65, 0
	s_cmp_lg_u32 s17, s71
	s_cselect_b64 s[62:63], -1, 0
	s_and_b64 s[58:59], s[42:43], exec
	s_cselect_b32 s10, s55, s46
	s_cselect_b32 s11, s48, s47
	s_cselect_b32 s58, s49, s64
	s_cselect_b32 s59, s14, s65
	s_cmp_eq_u32 s17, s71
	s_cselect_b32 s61, s11, s1
	s_cselect_b32 s60, s10, s0
	s_cselect_b32 s59, s59, s45
	s_cselect_b32 s58, s58, s44
	s_add_u32 s64, s46, 0x80
	s_addc_u32 s65, s47, 0
	v_add_u32_e32 v228, 0x10000, v252
	s_mov_b32 s77, -2
	s_mov_b64 s[64:65], 0
.LBB0_302:
	s_add_u32 s10, s46, s64
	s_addc_u32 s11, s47, s65
	s_add_u32 s100, s10, 0x80
	s_addc_u32 s101, s11, 0
	s_add_u32 s10, s10, 0x100
	s_addc_u32 s11, s11, 0
	s_add_u32 s66, vcc_lo, s64
	s_addc_u32 s67, vcc_hi, s65
	s_add_i32 s72, 0, 0x10000
	ds_read_b128 v[132:135], v228
	ds_read_b128 v[136:139], v228 offset:1024
	ds_read_b128 v[140:143], v228 offset:2048
	ds_read_b128 v[144:147], v228 offset:3072
	s_cmpk_eq_i32 s64, 0x700
	s_cselect_b32 s69, s61, s11
	s_cselect_b32 s68, s60, s10
	s_cselect_b32 s67, s59, s67
	s_cselect_b32 s66, s58, s66
	s_add_i32 m0, s12, 0xc000
	ds_read_b128 v[148:151], v241
	ds_read_b128 v[152:155], v241 offset:1024
	ds_read_b128 v[156:159], v241 offset:2048
	ds_read_b128 v[160:163], v241 offset:3072
	ds_read_b128 v[164:167], v241 offset:4096
	ds_read_b128 v[168:171], v241 offset:5120
	ds_read_b128 v[172:175], v241 offset:6144
	ds_read_b128 v[192:195], v241 offset:7168
	global_load_lds_dwordx4 v190, s[100:101]
	s_add_i32 m0, s12, 0xe000
	s_nop 0
	global_load_lds_dwordx4 v188, s[100:101]
	s_waitcnt lgkmcnt(8)
	s_barrier
	s_waitcnt lgkmcnt(0)
	v_mfma_f32_16x16x32_bf16 v[124:127], v[132:135], v[148:151], v[124:127]
	v_mfma_f32_16x16x32_bf16 v[120:123], v[140:143], v[148:151], v[120:123]
	v_mfma_f32_16x16x32_bf16 v[116:119], v[132:135], v[156:159], v[116:119]
	v_mfma_f32_16x16x32_bf16 v[112:115], v[140:143], v[156:159], v[112:115]
	v_mfma_f32_16x16x32_bf16 v[108:111], v[132:135], v[164:167], v[108:111]
	v_mfma_f32_16x16x32_bf16 v[104:107], v[140:143], v[164:167], v[104:107]
	v_mfma_f32_16x16x32_bf16 v[100:103], v[132:135], v[172:175], v[100:103]
	v_mfma_f32_16x16x32_bf16 v[96:99], v[140:143], v[172:175], v[96:99]
	v_mfma_f32_16x16x32_bf16 v[124:127], v[136:139], v[152:155], v[124:127]
	v_mfma_f32_16x16x32_bf16 v[120:123], v[144:147], v[152:155], v[120:123]
	v_mfma_f32_16x16x32_bf16 v[116:119], v[136:139], v[160:163], v[116:119]
	v_mfma_f32_16x16x32_bf16 v[112:115], v[144:147], v[160:163], v[112:115]
	v_mfma_f32_16x16x32_bf16 v[108:111], v[136:139], v[168:171], v[108:111]
	v_mfma_f32_16x16x32_bf16 v[104:107], v[144:147], v[168:171], v[104:107]
	v_mfma_f32_16x16x32_bf16 v[100:103], v[136:139], v[192:195], v[100:103]
	v_mfma_f32_16x16x32_bf16 v[96:99], v[144:147], v[192:195], v[96:99]
	s_barrier
	s_add_i32 s40, 0, 0x14000
	s_add_i32 s10, s72, s57
	s_mov_b32 m0, s10
	ds_read_b128 v[196:199], v228 offset:16384
	ds_read_b128 v[200:203], v228 offset:17408
	ds_read_b128 v[204:207], v228 offset:18432
	ds_read_b128 v[208:211], v228 offset:19456
	global_load_lds_dwordx4 v182, s[66:67]
	s_add_i32 m0, s10, 0x2000
	s_nop 0
	global_load_lds_dwordx4 v186, s[66:67]
	s_barrier
	s_waitcnt lgkmcnt(0)
	v_mfma_f32_16x16x32_bf16 v[60:63], v[196:199], v[148:151], v[60:63]
	v_mfma_f32_16x16x32_bf16 v[56:59], v[204:207], v[148:151], v[56:59]
	v_mfma_f32_16x16x32_bf16 v[52:55], v[196:199], v[156:159], v[52:55]
	v_mfma_f32_16x16x32_bf16 v[48:51], v[204:207], v[156:159], v[48:51]
	v_mfma_f32_16x16x32_bf16 v[44:47], v[196:199], v[164:167], v[44:47]
	v_mfma_f32_16x16x32_bf16 v[40:43], v[204:207], v[164:167], v[40:43]
	v_mfma_f32_16x16x32_bf16 v[36:39], v[196:199], v[172:175], v[36:39]
	v_mfma_f32_16x16x32_bf16 v[32:35], v[204:207], v[172:175], v[32:35]
	v_mfma_f32_16x16x32_bf16 v[60:63], v[200:203], v[152:155], v[60:63]
	v_mfma_f32_16x16x32_bf16 v[56:59], v[208:211], v[152:155], v[56:59]
	v_mfma_f32_16x16x32_bf16 v[52:55], v[200:203], v[160:163], v[52:55]
	v_mfma_f32_16x16x32_bf16 v[48:51], v[208:211], v[160:163], v[48:51]
	v_mfma_f32_16x16x32_bf16 v[44:47], v[200:203], v[168:171], v[44:47]
	v_mfma_f32_16x16x32_bf16 v[40:43], v[208:211], v[168:171], v[40:43]
	v_mfma_f32_16x16x32_bf16 v[36:39], v[200:203], v[192:195], v[36:39]
	v_mfma_f32_16x16x32_bf16 v[32:35], v[208:211], v[192:195], v[32:35]
	s_mov_b32 m0, s12
	s_barrier
	ds_read_b128 v[148:151], v241 offset:16384
	ds_read_b128 v[152:155], v241 offset:17408
	ds_read_b128 v[156:159], v241 offset:18432
	ds_read_b128 v[160:163], v241 offset:19456
	ds_read_b128 v[164:167], v241 offset:20480
	ds_read_b128 v[168:171], v241 offset:21504
	ds_read_b128 v[172:175], v241 offset:22528
	ds_read_b128 v[192:195], v241 offset:23552
	global_load_lds_dwordx4 v180, s[68:69]
	s_mov_b32 m0, s13
	s_nop 0
	global_load_lds_dwordx4 v184, s[68:69]
	s_barrier
	s_waitcnt lgkmcnt(0)
	v_mfma_f32_16x16x32_bf16 v[92:95], v[132:135], v[148:151], v[92:95]
	v_mfma_f32_16x16x32_bf16 v[88:91], v[140:143], v[148:151], v[88:91]
	v_mfma_f32_16x16x32_bf16 v[84:87], v[132:135], v[156:159], v[84:87]
	v_mfma_f32_16x16x32_bf16 v[80:83], v[140:143], v[156:159], v[80:83]
	v_mfma_f32_16x16x32_bf16 v[76:79], v[132:135], v[164:167], v[76:79]
	v_mfma_f32_16x16x32_bf16 v[72:75], v[140:143], v[164:167], v[72:75]
	v_mfma_f32_16x16x32_bf16 v[68:71], v[132:135], v[172:175], v[68:71]
	v_mfma_f32_16x16x32_bf16 v[64:67], v[140:143], v[172:175], v[64:67]
	v_mfma_f32_16x16x32_bf16 v[92:95], v[136:139], v[152:155], v[92:95]
	v_mfma_f32_16x16x32_bf16 v[88:91], v[144:147], v[152:155], v[88:91]
	v_mfma_f32_16x16x32_bf16 v[84:87], v[136:139], v[160:163], v[84:87]
	v_mfma_f32_16x16x32_bf16 v[80:83], v[144:147], v[160:163], v[80:83]
	v_mfma_f32_16x16x32_bf16 v[76:79], v[136:139], v[168:171], v[76:79]
	v_mfma_f32_16x16x32_bf16 v[72:75], v[144:147], v[168:171], v[72:75]
	v_mfma_f32_16x16x32_bf16 v[68:71], v[136:139], v[192:195], v[68:71]
	v_mfma_f32_16x16x32_bf16 v[64:67], v[144:147], v[192:195], v[64:67]
	s_barrier
; #define PG8_STAGE(bufoff, gbase, voff) do { _Pragma("unroll") for (int _i = 0; _i < 2; ++_i) \
;         __builtin_amdgcn_global_load_lds((const unsigned*)((const char*)(gbase) + (voff)[_i]), (LAS unsigned*)(lds + (bufoff) + ldsw + _i * 8192), 16, 0, 0); } while (0)
; #define PG8_LDA(dst, b, h) do { _Pragma("unroll") for (int m = 0; m < 4; ++m) _Pragma("unroll") for (int k = 0; k < 2; ++k) dst[m][k] = *(const LAS bf16x8*)(lds + PG8_SA(b, h) + aoff + m * 2048 + k * 1024); } while (0)
; #define PG8_LDB(dst, b, h) do { _Pragma("unroll") for (int n = 0; n < 2; ++n) _Pragma("unroll") for (int k = 0; k < 2; ++k) dst[n][k] = *(const LAS bf16x8*)(lds + PG8_SB(b, h) + boff + n * 2048 + k * 1024); } while (0)
; #define PG8_MMA(ai, bj, At, Bt) do { __builtin_amdgcn_s_setprio(1); _Pragma("unroll") for (int m = 0; m < 4; ++m) _Pragma("unroll") for (int n = 0; n < 2; ++n) _Pragma("unroll") for (int k = 0; k < 2; ++k) \
;         acc[ai][bj][m][n] = __builtin_amdgcn_mfma_f32_16x16x32_bf16(Bt[n][k], At[m][k], acc[ai][bj][m][n], 0, 0, 0); __builtin_amdgcn_s_setprio(0); } while (0)
; #define PG8_WAIT_V(n) asm volatile("s_waitcnt vmcnt(" #n ")" ::: "memory")
; #define PG8_WAIT_L(n) asm volatile("s_waitcnt lgkmcnt(" #n ")" ::: "memory")
; #define PG8_BAR __builtin_amdgcn_s_barrier()
; #define PG8_SCHED __builtin_amdgcn_sched_barrier(0)
; template <class Epi>
; __device__ __forceinline__ void gemm_phase(LAS unsigned char* lds, const Gemm g, const StaticOrder& S, const Epi& E) {
;     ...
;             PG8_WAIT_V(6); PG8_BAR; PG8_MMA(1, 1, At, B1); PG8_BAR;
;             PG8_LDB(B0, 1, 0); PG8_SCHED; PG8_LDA(At, 1, 0); PG8_STAGE(PG8_SA(0, 1), a2 + hstepA, voffA);
;             PG8_WAIT_L(8); PG8_BAR; PG8_WAIT_L(0); PG8_MMA(0, 0, At, B0); PG8_BAR; PG8_SCHED;
;             PG8_LDB(B1, 1, 1); PG8_STAGE(PG8_SB(1, 0), b3, voffB);
;             PG8_BAR; PG8_WAIT_L(0); PG8_MMA(0, 1, At, B1); PG8_BAR;
;             PG8_LDA(At, 1, 1); PG8_STAGE(PG8_SA(1, 0), a3, voffA);
;             PG8_BAR; PG8_WAIT_L(0); PG8_MMA(1, 0, At, B0); PG8_BAR; PG8_SCHED;
	s_add_u32 s10, s66, 0x40000
	s_addc_u32 s11, s67, 0
	s_add_i32 s40, s40, s57
	s_mov_b32 m0, s40
	s_nop 0
	global_load_lds_dwordx4 v182, s[10:11]
	s_add_i32 m0, s40, 0x2000
	s_nop 0
	global_load_lds_dwordx4 v186, s[10:11]
	s_waitcnt vmcnt(6)
	s_barrier
	v_mfma_f32_16x16x32_bf16 v[28:31], v[196:199], v[148:151], v[28:31]
	v_mfma_f32_16x16x32_bf16 v[24:27], v[204:207], v[148:151], v[24:27]
	v_mfma_f32_16x16x32_bf16 v[20:23], v[196:199], v[156:159], v[20:23]
	v_mfma_f32_16x16x32_bf16 v[16:19], v[204:207], v[156:159], v[16:19]
	v_mfma_f32_16x16x32_bf16 v[12:15], v[196:199], v[164:167], v[12:15]
	v_mfma_f32_16x16x32_bf16 v[8:11], v[204:207], v[164:167], v[8:11]
	v_mfma_f32_16x16x32_bf16 v[4:7], v[196:199], v[172:175], v[4:7]
	v_mfma_f32_16x16x32_bf16 v[0:3], v[204:207], v[172:175], v[0:3]
	v_mfma_f32_16x16x32_bf16 v[28:31], v[200:203], v[152:155], v[28:31]
	v_mfma_f32_16x16x32_bf16 v[24:27], v[208:211], v[152:155], v[24:27]
	v_mfma_f32_16x16x32_bf16 v[20:23], v[200:203], v[160:163], v[20:23]
	v_mfma_f32_16x16x32_bf16 v[16:19], v[208:211], v[160:163], v[16:19]
	v_mfma_f32_16x16x32_bf16 v[12:15], v[200:203], v[168:171], v[12:15]
	v_mfma_f32_16x16x32_bf16 v[8:11], v[208:211], v[168:171], v[8:11]
	v_mfma_f32_16x16x32_bf16 v[4:7], v[200:203], v[192:195], v[4:7]
	v_mfma_f32_16x16x32_bf16 v[0:3], v[208:211], v[192:195], v[0:3]
	s_add_i32 s40, 0, 0x18000
	s_barrier
	ds_read_b128 v[132:135], v228 offset:32768
	ds_read_b128 v[136:139], v228 offset:33792
	ds_read_b128 v[140:143], v228 offset:34816
	ds_read_b128 v[144:147], v228 offset:35840
	s_add_u32 s10, s68, s54
	s_addc_u32 s11, s69, 0
	s_mov_b32 m0, s4
	ds_read_b128 v[148:151], v241 offset:32768
	ds_read_b128 v[152:155], v241 offset:33792
	ds_read_b128 v[156:159], v241 offset:34816
	ds_read_b128 v[160:163], v241 offset:35840
	ds_read_b128 v[164:167], v241 offset:36864
	ds_read_b128 v[168:171], v241 offset:37888
	ds_read_b128 v[172:175], v241 offset:38912
	ds_read_b128 v[192:195], v241 offset:39936
	global_load_lds_dwordx4 v180, s[10:11]
	s_mov_b32 m0, s70
	s_nop 0
	global_load_lds_dwordx4 v184, s[10:11]
	s_waitcnt lgkmcnt(8)
	s_barrier
	s_waitcnt lgkmcnt(0)
	v_mfma_f32_16x16x32_bf16 v[124:127], v[132:135], v[148:151], v[124:127]
	v_mfma_f32_16x16x32_bf16 v[120:123], v[140:143], v[148:151], v[120:123]
	v_mfma_f32_16x16x32_bf16 v[116:119], v[132:135], v[156:159], v[116:119]
	v_mfma_f32_16x16x32_bf16 v[112:115], v[140:143], v[156:159], v[112:115]
	v_mfma_f32_16x16x32_bf16 v[108:111], v[132:135], v[164:167], v[108:111]
	v_mfma_f32_16x16x32_bf16 v[104:107], v[140:143], v[164:167], v[104:107]
	v_mfma_f32_16x16x32_bf16 v[100:103], v[132:135], v[172:175], v[100:103]
	v_mfma_f32_16x16x32_bf16 v[96:99], v[140:143], v[172:175], v[96:99]
	v_mfma_f32_16x16x32_bf16 v[124:127], v[136:139], v[152:155], v[124:127]
	v_mfma_f32_16x16x32_bf16 v[120:123], v[144:147], v[152:155], v[120:123]
	v_mfma_f32_16x16x32_bf16 v[116:119], v[136:139], v[160:163], v[116:119]
	v_mfma_f32_16x16x32_bf16 v[112:115], v[144:147], v[160:163], v[112:115]
	v_mfma_f32_16x16x32_bf16 v[108:111], v[136:139], v[168:171], v[108:111]
	v_mfma_f32_16x16x32_bf16 v[104:107], v[144:147], v[168:171], v[104:107]
	v_mfma_f32_16x16x32_bf16 v[100:103], v[136:139], v[192:195], v[100:103]
	v_mfma_f32_16x16x32_bf16 v[96:99], v[144:147], v[192:195], v[96:99]
	s_barrier
	s_add_i32 s41, 0, 0x1c000
	s_add_i32 s10, s40, s57
	s_add_u32 s100, s66, 0x80
	s_addc_u32 s101, s67, 0
	s_mov_b32 m0, s10
	ds_read_b128 v[196:199], v228 offset:49152
	ds_read_b128 v[200:203], v228 offset:50176
	ds_read_b128 v[204:207], v228 offset:51200
	ds_read_b128 v[208:211], v228 offset:52224
	global_load_lds_dwordx4 v182, s[100:101]
	s_add_i32 m0, s10, 0x2000
	s_nop 0
	global_load_lds_dwordx4 v186, s[100:101]
	s_barrier
	s_waitcnt lgkmcnt(0)
	v_mfma_f32_16x16x32_bf16 v[60:63], v[196:199], v[148:151], v[60:63]
	v_mfma_f32_16x16x32_bf16 v[56:59], v[204:207], v[148:151], v[56:59]
	v_mfma_f32_16x16x32_bf16 v[52:55], v[196:199], v[156:159], v[52:55]
	v_mfma_f32_16x16x32_bf16 v[48:51], v[204:207], v[156:159], v[48:51]
	v_mfma_f32_16x16x32_bf16 v[44:47], v[196:199], v[164:167], v[44:47]
	v_mfma_f32_16x16x32_bf16 v[40:43], v[204:207], v[164:167], v[40:43]
	v_mfma_f32_16x16x32_bf16 v[36:39], v[196:199], v[172:175], v[36:39]
	v_mfma_f32_16x16x32_bf16 v[32:35], v[204:207], v[172:175], v[32:35]
	v_mfma_f32_16x16x32_bf16 v[60:63], v[200:203], v[152:155], v[60:63]
	v_mfma_f32_16x16x32_bf16 v[56:59], v[208:211], v[152:155], v[56:59]
	v_mfma_f32_16x16x32_bf16 v[52:55], v[200:203], v[160:163], v[52:55]
	v_mfma_f32_16x16x32_bf16 v[48:51], v[208:211], v[160:163], v[48:51]
	v_mfma_f32_16x16x32_bf16 v[44:47], v[200:203], v[168:171], v[44:47]
	v_mfma_f32_16x16x32_bf16 v[40:43], v[208:211], v[168:171], v[40:43]
	v_mfma_f32_16x16x32_bf16 v[36:39], v[200:203], v[192:195], v[36:39]
	v_mfma_f32_16x16x32_bf16 v[32:35], v[208:211], v[192:195], v[32:35]
	s_mov_b32 m0, s6
	s_add_u32 s100, s68, 0x80
	s_addc_u32 s101, s69, 0
	s_barrier
	ds_read_b128 v[148:151], v241 offset:49152
	ds_read_b128 v[152:155], v241 offset:50176
	ds_read_b128 v[156:159], v241 offset:51200
	ds_read_b128 v[160:163], v241 offset:52224
	ds_read_b128 v[164:167], v241 offset:53248
	ds_read_b128 v[168:171], v241 offset:54272
	ds_read_b128 v[172:175], v241 offset:55296
	ds_read_b128 v[192:195], v241 offset:56320
	global_load_lds_dwordx4 v180, s[100:101]
	s_mov_b32 m0, s78
	s_nop 0
	global_load_lds_dwordx4 v184, s[100:101]
	s_barrier
; __device__ __forceinline__ float bf_lo(unsigned u) { return __uint_as_float(u << 16); }
; __device__ __forceinline__ float bf_hi(unsigned u) { return __uint_as_float(u & 0xffff0000u); }
; #define PG8_STAGE(bufoff, gbase, voff) do { _Pragma("unroll") for (int _i = 0; _i < 2; ++_i) \
;         __builtin_amdgcn_global_load_lds((const unsigned*)((const char*)(gbase) + (voff)[_i]), (LAS unsigned*)(lds + (bufoff) + ldsw + _i * 8192), 16, 0, 0); } while (0)
; #define PG8_LDA(dst, b, h) do { _Pragma("unroll") for (int m = 0; m < 4; ++m) _Pragma("unroll") for (int k = 0; k < 2; ++k) dst[m][k] = *(const LAS bf16x8*)(lds + PG8_SA(b, h) + aoff + m * 2048 + k * 1024); } while (0)
; #define PG8_WAIT_V(n) asm volatile("s_waitcnt vmcnt(" #n ")" ::: "memory")
; #define PG8_WAIT_L(n) asm volatile("s_waitcnt lgkmcnt(" #n ")" ::: "memory")
; #define PG8_BAR __builtin_amdgcn_s_barrier()
; template <class Epi>
; __device__ __forceinline__ void gemm_phase(LAS unsigned char* lds, const Gemm g, const StaticOrder& S, const Epi& E) {
;     ...
;             PG8_BAR; PG8_WAIT_L(0); PG8_MMA(0, 1, At, B1); PG8_BAR;
;             PG8_LDA(At, 1, 1); PG8_STAGE(PG8_SA(1, 0), a3, voffA);
;             PG8_BAR; PG8_WAIT_L(0); PG8_MMA(1, 0, At, B0); PG8_BAR; PG8_SCHED;
;             PG8_STAGE(PG8_SB(1, 1), b3 + hstepB, voffB);
;             PG8_WAIT_V(6); PG8_BAR; PG8_MMA(1, 1, At, B1); PG8_BAR;
;         }
;         if (!lastpass) { E.mid(acc, cur, wr, wc, fr, fq); cA = nA; cB = nB; }
;     __device__ __forceinline__ void mid(f32x4 (&acc)[2][2][4][2], const pg8::Unit& u, int wr, int wc, int fr_in, int fq_in) const {
;         int fr = fr_in, fq = fq_in; asm volatile("" : "+v"(fr), "+v"(fq));
;         const int row0 = u.pm * 256 + wr * 64 + fr, col0 = u.pn * 256 + wc * 32 + 8 * fq;
; #pragma unroll
;         for (int i = 0; i < 16; ++i) { const int ai = i >> 3, m = (i >> 1) & 3, bj = i & 1; const int n = col0 + bj * 128;
;             const u32x4 gq = *(const u32x4*)(proj + (size_t)(row0 + ai * 128 + m * 16) * NC1 + C_MG + (n >> 7) * 256 + (n & 127));
;             acc[ai][bj][m][0][0] *= bf_lo(gq.x); acc[ai][bj][m][0][1] *= bf_hi(gq.x); acc[ai][bj][m][0][2] *= bf_lo(gq.y); acc[ai][bj][m][0][3] *= bf_hi(gq.y);
;             acc[ai][bj][m][1][0] *= bf_lo(gq.z); acc[ai][bj][m][1][1] *= bf_hi(gq.z); acc[ai][bj][m][1][2] *= bf_lo(gq.w); acc[ai][bj][m][1][3] *= bf_hi(gq.w); }
	s_waitcnt lgkmcnt(0)
	v_mfma_f32_16x16x32_bf16 v[92:95], v[132:135], v[148:151], v[92:95]
	v_mfma_f32_16x16x32_bf16 v[88:91], v[140:143], v[148:151], v[88:91]
	v_mfma_f32_16x16x32_bf16 v[84:87], v[132:135], v[156:159], v[84:87]
	v_mfma_f32_16x16x32_bf16 v[80:83], v[140:143], v[156:159], v[80:83]
	v_mfma_f32_16x16x32_bf16 v[76:79], v[132:135], v[164:167], v[76:79]
	v_mfma_f32_16x16x32_bf16 v[72:75], v[140:143], v[164:167], v[72:75]
	v_mfma_f32_16x16x32_bf16 v[68:71], v[132:135], v[172:175], v[68:71]
	v_mfma_f32_16x16x32_bf16 v[64:67], v[140:143], v[172:175], v[64:67]
	v_mfma_f32_16x16x32_bf16 v[92:95], v[136:139], v[152:155], v[92:95]
	v_mfma_f32_16x16x32_bf16 v[88:91], v[144:147], v[152:155], v[88:91]
	v_mfma_f32_16x16x32_bf16 v[84:87], v[136:139], v[160:163], v[84:87]
	v_mfma_f32_16x16x32_bf16 v[80:83], v[144:147], v[160:163], v[80:83]
	v_mfma_f32_16x16x32_bf16 v[76:79], v[136:139], v[168:171], v[76:79]
	v_mfma_f32_16x16x32_bf16 v[72:75], v[144:147], v[168:171], v[72:75]
	v_mfma_f32_16x16x32_bf16 v[68:71], v[136:139], v[192:195], v[68:71]
	v_mfma_f32_16x16x32_bf16 v[64:67], v[144:147], v[192:195], v[64:67]
	s_barrier
	s_add_u32 s10, s66, 0x40080
	s_addc_u32 s11, s67, 0
	s_add_i32 s40, s41, s57
	s_mov_b32 m0, s40
	s_nop 0
	global_load_lds_dwordx4 v182, s[10:11]
	s_add_i32 m0, s40, 0x2000
	s_nop 0
	global_load_lds_dwordx4 v186, s[10:11]
	s_waitcnt vmcnt(6)
	s_barrier
	v_mfma_f32_16x16x32_bf16 v[28:31], v[196:199], v[148:151], v[28:31]
	v_mfma_f32_16x16x32_bf16 v[24:27], v[204:207], v[148:151], v[24:27]
	v_mfma_f32_16x16x32_bf16 v[20:23], v[196:199], v[156:159], v[20:23]
	v_mfma_f32_16x16x32_bf16 v[16:19], v[204:207], v[156:159], v[16:19]
	v_mfma_f32_16x16x32_bf16 v[12:15], v[196:199], v[164:167], v[12:15]
	v_mfma_f32_16x16x32_bf16 v[8:11], v[204:207], v[164:167], v[8:11]
	v_mfma_f32_16x16x32_bf16 v[4:7], v[196:199], v[172:175], v[4:7]
	v_mfma_f32_16x16x32_bf16 v[0:3], v[204:207], v[172:175], v[0:3]
	v_mfma_f32_16x16x32_bf16 v[28:31], v[200:203], v[152:155], v[28:31]
	v_mfma_f32_16x16x32_bf16 v[24:27], v[208:211], v[152:155], v[24:27]
	v_mfma_f32_16x16x32_bf16 v[20:23], v[200:203], v[160:163], v[20:23]
	v_mfma_f32_16x16x32_bf16 v[16:19], v[208:211], v[160:163], v[16:19]
	v_mfma_f32_16x16x32_bf16 v[12:15], v[200:203], v[168:171], v[12:15]
	v_mfma_f32_16x16x32_bf16 v[8:11], v[208:211], v[168:171], v[8:11]
	v_mfma_f32_16x16x32_bf16 v[4:7], v[200:203], v[192:195], v[4:7]
	v_mfma_f32_16x16x32_bf16 v[0:3], v[208:211], v[192:195], v[0:3]
	s_add_i32 s77, s77, 2
	s_add_u32 s64, s64, 0x100
	s_addc_u32 s65, s65, 0
	s_cmp_gt_u32 s77, 13
	s_barrier
	s_cbranch_scc0 .LBB0_302
	s_add_u32 s64, vcc_lo, 0xffffff00
	s_addc_u32 s65, vcc_hi, -1
	s_and_b64 vcc, exec, s[62:63]
	s_cbranch_vccz .LBB0_300
	v_mov_b32_e32 v128, v251
	v_mov_b32_e32 v129, v179
	v_mov_b64_e32 v[130:131], s[98:99]
	v_lshl_add_u32 v128, v128, 3, s16
	v_lshlrev_b32_e32 v132, 1, v128
	v_add_u32_e32 v134, s15, v129
	v_and_b32_e32 v140, 0xffffff00, v132
	v_and_b32_e32 v135, 0x78, v128
	v_mad_i64_i32 v[128:129], s[10:11], v134, s22, v[130:131]
	v_ashrrev_i32_e32 v141, 31, v140
	v_lshl_add_u64 v[128:129], v[128:129], 0, s[34:35]
	v_lshlrev_b64 v[132:133], 1, v[140:141]
	v_lshlrev_b32_e32 v176, 1, v135
	v_lshl_add_u64 v[128:129], v[128:129], 0, v[132:133]
	v_lshl_add_u64 v[128:129], v[128:129], 0, v[176:177]
	s_mov_b64 s[64:65], s[44:45]
	s_mov_b64 s[46:47], s[0:1]
	s_mov_b64 s[100:101], 0x50000
	global_load_dwordx4 v[132:135], v[128:129], off
	global_load_dwordx4 v[136:139], v[128:129], off offset:512
	v_lshl_add_u64 v[130:131], v[128:129], 0, s[100:101]
	global_load_dwordx4 v[140:143], v[130:131], off
	global_load_dwordx4 v[144:147], v[130:131], off offset:512
	v_lshl_add_u64 v[130:131], v[130:131], 0, s[100:101]
	global_load_dwordx4 v[148:151], v[130:131], off
	global_load_dwordx4 v[152:155], v[130:131], off offset:512
	v_lshl_add_u64 v[130:131], v[130:131], 0, s[100:101]
	global_load_dwordx4 v[156:159], v[130:131], off
	global_load_dwordx4 v[160:163], v[130:131], off offset:512
	s_mov_b64 s[100:101], 0x280000
	v_lshl_add_u64 v[130:131], v[128:129], 0, s[100:101]
	s_mov_b64 s[100:101], 0x50000
	global_load_dwordx4 v[164:167], v[130:131], off
	global_load_dwordx4 v[168:171], v[130:131], off offset:512
	v_lshl_add_u64 v[130:131], v[130:131], 0, s[100:101]
	global_load_dwordx4 v[172:175], v[130:131], off
	global_load_dwordx4 v[192:195], v[130:131], off offset:512
	v_lshl_add_u64 v[130:131], v[130:131], 0, s[100:101]
	global_load_dwordx4 v[196:199], v[130:131], off
	global_load_dwordx4 v[200:203], v[130:131], off offset:512
	v_lshl_add_u64 v[130:131], v[130:131], 0, s[100:101]
	global_load_dwordx4 v[204:207], v[130:131], off
	global_load_dwordx4 v[208:211], v[130:131], off offset:512
	s_waitcnt vmcnt(15)
	v_lshlrev_b32_e32 v128, 16, v132
	v_and_b32_e32 v129, 0xffff0000, v132
	v_lshlrev_b32_e32 v130, 16, v133
	v_and_b32_e32 v131, 0xffff0000, v133
	v_pk_mul_f32 v[124:125], v[124:125], v[128:129]
	v_pk_mul_f32 v[126:127], v[126:127], v[130:131]
	v_lshlrev_b32_e32 v128, 16, v134
	v_and_b32_e32 v129, 0xffff0000, v134
	v_lshlrev_b32_e32 v130, 16, v135
	v_and_b32_e32 v131, 0xffff0000, v135
	v_pk_mul_f32 v[120:121], v[120:121], v[128:129]
	v_pk_mul_f32 v[122:123], v[122:123], v[130:131]
	s_waitcnt vmcnt(14)
	v_lshlrev_b32_e32 v128, 16, v136
	v_and_b32_e32 v129, 0xffff0000, v136
	v_lshlrev_b32_e32 v130, 16, v137
	v_and_b32_e32 v131, 0xffff0000, v137
	v_pk_mul_f32 v[60:61], v[60:61], v[128:129]
	v_pk_mul_f32 v[62:63], v[62:63], v[130:131]
	v_lshlrev_b32_e32 v128, 16, v138
	v_and_b32_e32 v129, 0xffff0000, v138
	v_lshlrev_b32_e32 v130, 16, v139
	v_and_b32_e32 v131, 0xffff0000, v139
	v_pk_mul_f32 v[56:57], v[56:57], v[128:129]
	v_pk_mul_f32 v[58:59], v[58:59], v[130:131]
	s_waitcnt vmcnt(13)
; __device__ __forceinline__ float bf_lo(unsigned u) { return __uint_as_float(u << 16); }
; __device__ __forceinline__ float bf_hi(unsigned u) { return __uint_as_float(u & 0xffff0000u); }
;     __device__ __forceinline__ void mid(f32x4 (&acc)[2][2][4][2], const pg8::Unit& u, int wr, int wc, int fr_in, int fq_in) const {
;     ...
;         for (int i = 0; i < 16; ++i) { const int ai = i >> 3, m = (i >> 1) & 3, bj = i & 1; const int n = col0 + bj * 128;
;             const u32x4 gq = *(const u32x4*)(proj + (size_t)(row0 + ai * 128 + m * 16) * NC1 + C_MG + (n >> 7) * 256 + (n & 127));
;             acc[ai][bj][m][0][0] *= bf_lo(gq.x); acc[ai][bj][m][0][1] *= bf_hi(gq.x); acc[ai][bj][m][0][2] *= bf_lo(gq.y); acc[ai][bj][m][0][3] *= bf_hi(gq.y);
;             acc[ai][bj][m][1][0] *= bf_lo(gq.z); acc[ai][bj][m][1][1] *= bf_hi(gq.z); acc[ai][bj][m][1][2] *= bf_lo(gq.w); acc[ai][bj][m][1][3] *= bf_hi(gq.w); }
	v_lshlrev_b32_e32 v128, 16, v140
	v_and_b32_e32 v129, 0xffff0000, v140
	v_lshlrev_b32_e32 v130, 16, v141
	v_and_b32_e32 v131, 0xffff0000, v141
	v_pk_mul_f32 v[116:117], v[116:117], v[128:129]
	v_pk_mul_f32 v[118:119], v[118:119], v[130:131]
	v_lshlrev_b32_e32 v128, 16, v142
	v_and_b32_e32 v129, 0xffff0000, v142
	v_lshlrev_b32_e32 v130, 16, v143
	v_and_b32_e32 v131, 0xffff0000, v143
	v_pk_mul_f32 v[112:113], v[112:113], v[128:129]
	v_pk_mul_f32 v[114:115], v[114:115], v[130:131]
	s_waitcnt vmcnt(12)
	v_lshlrev_b32_e32 v128, 16, v144
	v_and_b32_e32 v129, 0xffff0000, v144
	v_lshlrev_b32_e32 v130, 16, v145
	v_and_b32_e32 v131, 0xffff0000, v145
	v_pk_mul_f32 v[52:53], v[52:53], v[128:129]
	v_pk_mul_f32 v[54:55], v[54:55], v[130:131]
	v_lshlrev_b32_e32 v128, 16, v146
	v_and_b32_e32 v129, 0xffff0000, v146
	v_lshlrev_b32_e32 v130, 16, v147
	v_and_b32_e32 v131, 0xffff0000, v147
	v_pk_mul_f32 v[48:49], v[48:49], v[128:129]
	v_pk_mul_f32 v[50:51], v[50:51], v[130:131]
	s_waitcnt vmcnt(11)
	v_lshlrev_b32_e32 v128, 16, v148
	v_and_b32_e32 v129, 0xffff0000, v148
	v_lshlrev_b32_e32 v130, 16, v149
	v_and_b32_e32 v131, 0xffff0000, v149
	v_pk_mul_f32 v[108:109], v[108:109], v[128:129]
	v_pk_mul_f32 v[110:111], v[110:111], v[130:131]
	v_lshlrev_b32_e32 v128, 16, v150
	v_and_b32_e32 v129, 0xffff0000, v150
	v_lshlrev_b32_e32 v130, 16, v151
	v_and_b32_e32 v131, 0xffff0000, v151
	v_pk_mul_f32 v[104:105], v[104:105], v[128:129]
	v_pk_mul_f32 v[106:107], v[106:107], v[130:131]
	s_waitcnt vmcnt(10)
	v_lshlrev_b32_e32 v128, 16, v152
	v_and_b32_e32 v129, 0xffff0000, v152
	v_lshlrev_b32_e32 v130, 16, v153
	v_and_b32_e32 v131, 0xffff0000, v153
	v_pk_mul_f32 v[44:45], v[44:45], v[128:129]
	v_pk_mul_f32 v[46:47], v[46:47], v[130:131]
	v_lshlrev_b32_e32 v128, 16, v154
	v_and_b32_e32 v129, 0xffff0000, v154
	v_lshlrev_b32_e32 v130, 16, v155
	v_and_b32_e32 v131, 0xffff0000, v155
	v_pk_mul_f32 v[40:41], v[40:41], v[128:129]
	v_pk_mul_f32 v[42:43], v[42:43], v[130:131]
	s_waitcnt vmcnt(9)
	v_lshlrev_b32_e32 v128, 16, v156
	v_and_b32_e32 v129, 0xffff0000, v156
	v_lshlrev_b32_e32 v130, 16, v157
	v_and_b32_e32 v131, 0xffff0000, v157
	v_pk_mul_f32 v[100:101], v[100:101], v[128:129]
	v_pk_mul_f32 v[102:103], v[102:103], v[130:131]
	v_lshlrev_b32_e32 v128, 16, v158
	v_and_b32_e32 v129, 0xffff0000, v158
	v_lshlrev_b32_e32 v130, 16, v159
	v_and_b32_e32 v131, 0xffff0000, v159
	v_pk_mul_f32 v[96:97], v[96:97], v[128:129]
	v_pk_mul_f32 v[98:99], v[98:99], v[130:131]
	s_waitcnt vmcnt(8)
	v_lshlrev_b32_e32 v128, 16, v160
	v_and_b32_e32 v129, 0xffff0000, v160
	v_lshlrev_b32_e32 v130, 16, v161
	v_and_b32_e32 v131, 0xffff0000, v161
	v_pk_mul_f32 v[36:37], v[36:37], v[128:129]
	v_pk_mul_f32 v[38:39], v[38:39], v[130:131]
	v_lshlrev_b32_e32 v128, 16, v162
	v_and_b32_e32 v129, 0xffff0000, v162
	v_lshlrev_b32_e32 v130, 16, v163
	v_and_b32_e32 v131, 0xffff0000, v163
	v_pk_mul_f32 v[32:33], v[32:33], v[128:129]
	v_pk_mul_f32 v[34:35], v[34:35], v[130:131]
	s_waitcnt vmcnt(7)
	v_lshlrev_b32_e32 v128, 16, v164
	v_and_b32_e32 v129, 0xffff0000, v164
	v_lshlrev_b32_e32 v130, 16, v165
	v_and_b32_e32 v131, 0xffff0000, v165
	v_pk_mul_f32 v[92:93], v[92:93], v[128:129]
	v_pk_mul_f32 v[94:95], v[94:95], v[130:131]
	v_lshlrev_b32_e32 v128, 16, v166
	v_and_b32_e32 v129, 0xffff0000, v166
	v_lshlrev_b32_e32 v130, 16, v167
	v_and_b32_e32 v131, 0xffff0000, v167
	v_pk_mul_f32 v[88:89], v[88:89], v[128:129]
	v_pk_mul_f32 v[90:91], v[90:91], v[130:131]
	s_waitcnt vmcnt(6)
	v_lshlrev_b32_e32 v128, 16, v168
	v_and_b32_e32 v129, 0xffff0000, v168
	v_lshlrev_b32_e32 v130, 16, v169
	v_and_b32_e32 v131, 0xffff0000, v169
	v_pk_mul_f32 v[28:29], v[28:29], v[128:129]
	v_pk_mul_f32 v[30:31], v[30:31], v[130:131]
	v_lshlrev_b32_e32 v128, 16, v170
	v_and_b32_e32 v129, 0xffff0000, v170
	v_lshlrev_b32_e32 v130, 16, v171
	v_and_b32_e32 v131, 0xffff0000, v171
	v_pk_mul_f32 v[24:25], v[24:25], v[128:129]
	v_pk_mul_f32 v[26:27], v[26:27], v[130:131]
	s_waitcnt vmcnt(5)
	v_lshlrev_b32_e32 v128, 16, v172
	v_and_b32_e32 v129, 0xffff0000, v172
	v_lshlrev_b32_e32 v130, 16, v173
	v_and_b32_e32 v131, 0xffff0000, v173
	v_pk_mul_f32 v[84:85], v[84:85], v[128:129]
	v_pk_mul_f32 v[86:87], v[86:87], v[130:131]
	v_lshlrev_b32_e32 v128, 16, v174
	v_and_b32_e32 v129, 0xffff0000, v174
	v_lshlrev_b32_e32 v130, 16, v175
	v_and_b32_e32 v131, 0xffff0000, v175
	v_pk_mul_f32 v[80:81], v[80:81], v[128:129]
	v_pk_mul_f32 v[82:83], v[82:83], v[130:131]
	s_waitcnt vmcnt(4)
	v_lshlrev_b32_e32 v128, 16, v192
	v_and_b32_e32 v129, 0xffff0000, v192
	v_lshlrev_b32_e32 v130, 16, v193
	v_and_b32_e32 v131, 0xffff0000, v193
	v_pk_mul_f32 v[20:21], v[20:21], v[128:129]
	v_pk_mul_f32 v[22:23], v[22:23], v[130:131]
	v_lshlrev_b32_e32 v128, 16, v194
	v_and_b32_e32 v129, 0xffff0000, v194
	v_lshlrev_b32_e32 v130, 16, v195
	v_and_b32_e32 v131, 0xffff0000, v195
	v_pk_mul_f32 v[16:17], v[16:17], v[128:129]
	v_pk_mul_f32 v[18:19], v[18:19], v[130:131]
	s_waitcnt vmcnt(3)
	v_lshlrev_b32_e32 v128, 16, v196
	v_and_b32_e32 v129, 0xffff0000, v196
	v_lshlrev_b32_e32 v130, 16, v197
	v_and_b32_e32 v131, 0xffff0000, v197
	v_pk_mul_f32 v[76:77], v[76:77], v[128:129]
	v_pk_mul_f32 v[78:79], v[78:79], v[130:131]
	v_lshlrev_b32_e32 v128, 16, v198
	v_and_b32_e32 v129, 0xffff0000, v198
	v_lshlrev_b32_e32 v130, 16, v199
	v_and_b32_e32 v131, 0xffff0000, v199
	v_pk_mul_f32 v[72:73], v[72:73], v[128:129]
	v_pk_mul_f32 v[74:75], v[74:75], v[130:131]
	s_waitcnt vmcnt(2)
	v_lshlrev_b32_e32 v128, 16, v200
	v_and_b32_e32 v129, 0xffff0000, v200
	v_lshlrev_b32_e32 v130, 16, v201
	v_and_b32_e32 v131, 0xffff0000, v201
	v_pk_mul_f32 v[12:13], v[12:13], v[128:129]
	v_pk_mul_f32 v[14:15], v[14:15], v[130:131]
	v_lshlrev_b32_e32 v128, 16, v202
	v_and_b32_e32 v129, 0xffff0000, v202
	v_lshlrev_b32_e32 v130, 16, v203
	v_and_b32_e32 v131, 0xffff0000, v203
	v_pk_mul_f32 v[8:9], v[8:9], v[128:129]
	v_pk_mul_f32 v[10:11], v[10:11], v[130:131]
	s_waitcnt vmcnt(1)
	v_lshlrev_b32_e32 v128, 16, v204
	v_and_b32_e32 v129, 0xffff0000, v204
	v_lshlrev_b32_e32 v130, 16, v205
	v_and_b32_e32 v131, 0xffff0000, v205
	v_pk_mul_f32 v[68:69], v[68:69], v[128:129]
	v_pk_mul_f32 v[70:71], v[70:71], v[130:131]
	v_lshlrev_b32_e32 v128, 16, v206
	v_and_b32_e32 v129, 0xffff0000, v206
	v_lshlrev_b32_e32 v130, 16, v207
	v_and_b32_e32 v131, 0xffff0000, v207
	v_pk_mul_f32 v[64:65], v[64:65], v[128:129]
	v_pk_mul_f32 v[66:67], v[66:67], v[130:131]
	s_waitcnt vmcnt(0)
	v_lshlrev_b32_e32 v128, 16, v208
	v_and_b32_e32 v129, 0xffff0000, v208
	v_lshlrev_b32_e32 v130, 16, v209
	v_and_b32_e32 v131, 0xffff0000, v209
	v_pk_mul_f32 v[4:5], v[4:5], v[128:129]
	v_pk_mul_f32 v[6:7], v[6:7], v[130:131]
	v_lshlrev_b32_e32 v128, 16, v210
	v_and_b32_e32 v129, 0xffff0000, v210
	v_lshlrev_b32_e32 v130, 16, v211
	v_and_b32_e32 v131, 0xffff0000, v211
	v_pk_mul_f32 v[0:1], v[0:1], v[128:129]
	v_pk_mul_f32 v[2:3], v[2:3], v[130:131]
	s_branch .LBB0_300
